# GDN segment (vi): 16 operand reads issued up front into fresh VGPRs, 8 MFMAs with counted lgkmcnt waits, then W-row negate/convert/writes
# speedup vs baseline: 1.0027x; 1.0013x over previous
; __device__ __forceinline__ void phase_gdn2(Frame& F, bool ctx_out, bool dry = false) {
;     ...
;                 f32x4 U[4];
; #pragma unroll
;                 for (int I = 0; I < 4; ++I) {
;                     const hb8 fa = *(const LAS hb8*)(TUB + (I * 16 + l15) * GB + q4 * 8), fb = *(const LAS hb8*)(VT + (vb * 16 + l15) * GT + I * 16 + q4 * 8);
;                     U[I] = MFMA16(fa, fb, ((f32x4){0.f, 0.f, 0.f, 0.f}));
;                     const hb8 ga = *(const LAS hb8*)(KCT + (vb * 16 + l15) * GT + I * 16 + q4 * 8), gbv = *(const LAS hb8*)(TWB + (I * 16 + l15) * GB + q4 * 8);
;                     const f32x4 wt = MFMA16(ga, gbv, ((f32x4){0.f, 0.f, 0.f, 0.f}));
;                     *(LAS v2u*)(W + (I * 16 + l15) * GS + vb * 16 + q4 * 4) = (v2u){pk2(-wt.x, -wt.y), pk2(-wt.z, -wt.w)};
;                 }
;                 LDS_WAIT(); asm volatile("" ::: "memory");
;                 LDS_BARRIER();
; #pragma unroll
;                 for (int I = 0; I < 4; ++I) {
;                     f32x4 vn = U[I], oa = (f32x4){0.f, 0.f, 0.f, 0.f};
; #pragma unroll
;                     for (int ks = 0; ks < 4; ++ks) {
;                         const v4u sb4 = (v4u){pk2(S[2 * ks].x, S[2 * ks].y), pk2(S[2 * ks].z, S[2 * ks].w), pk2(S[2 * ks + 1].x, S[2 * ks + 1].y), pk2(S[2 * ks + 1].z, S[2 * ks + 1].w)};
;                         const hb8 fb = __builtin_bit_cast(hb8, sb4);
;                         const v2u w0 = *(const LAS v2u*)(W + (I * 16 + l15) * GS + ks * 32 + q4 * 4), w1 = *(const LAS v2u*)(W + (I * 16 + l15) * GS + ks * 32 + 16 + q4 * 4);
;                         const v2u q0 = *(const LAS v2u*)(QC + (I * 16 + l15) * GS + ks * 32 + q4 * 4), q1 = *(const LAS v2u*)(QC + (I * 16 + l15) * GS + ks * 32 + 16 + q4 * 4);
;                         const v4u fw4 = (v4u){w0.x, w0.y, w1.x, w1.y}, fq4 = (v4u){q0.x, q0.y, q1.x, q1.y};
;                         vn = MFMA16(__builtin_bit_cast(hb8, fw4), fb, vn); oa = MFMA16(__builtin_bit_cast(hb8, fq4), fb, oa); }
;                     const f32x4 ck = *(const LAS f32x4*)(s_ckd + I * 16 + q4 * 4), eg = *(const LAS f32x4*)(s_eG + I * 16 + q4 * 4), rqv = *(const LAS f32x4*)(s_rq + I * 16 + q4 * 4);
;                     const v4u vn4 = (v4u){pk2(vn.x, vn.y), pk2(vn.z, vn.w), 0u, 0u}, vp4 = (v4u){pk2(vn.x * ck.x, vn.y * ck.y), pk2(vn.z * ck.z, vn.w * ck.w), 0u, 0u};
;                     oa = oa * eg;
.Lgdn_drained:
	v_add3_u32 v88, s0, v0, v1
	v_add3_u32 v89, s47, v0, v1
	ds_read_b128 v[154:157], v88
	ds_read_b128 v[158:161], v3 offset:55296
	ds_read_b128 v[162:165], v3 offset:34816
	ds_read_b128 v[166:169], v89
	ds_read_b128 v[170:173], v88 offset:1280
	ds_read_b128 v[174:177], v3 offset:55328
	ds_read_b128 v[178:181], v3 offset:34848
	ds_read_b128 v[182:185], v89 offset:1280
	ds_read_b128 v[186:189], v88 offset:2560
	ds_read_b128 v[190:193], v3 offset:55360
	ds_read_b128 v[194:197], v3 offset:34880
	ds_read_b128 v[198:201], v89 offset:2560
	ds_read_b128 v[202:205], v88 offset:3840
	ds_read_b128 v[206:209], v3 offset:55392
	ds_read_b128 v[210:213], v3 offset:34912
	ds_read_b128 v[214:217], v89 offset:3840
	v_add_u32_e32 v108, 0, v139
	v_add_u32_e32 v107, s76, v140
	v_add_u32_e32 v101, s85, v139
	v_mul_u32_u24_e32 v84, 0x110, v137
	v_add3_u32 v92, s67, v139, v84
	v_mad_u32_u24 v103, v137, s10, v108
	v_or_b32_e32 v110, 16, v137
	v_mad_u32_u24 v104, v110, s10, v108
	v_or_b32_e32 v109, 32, v137
	v_or_b32_e32 v100, 48, v137
	s_add_i32 s56, s56, 1
	s_add_i32 s3, s3, 64
	s_add_i32 s96, s96, 1
	s_cmpk_eq_i32 s3, 0x900
	s_waitcnt lgkmcnt(14)
	v_mfma_f32_16x16x32_bf16 v[68:71], v[154:157], v[158:161], 0
	s_waitcnt lgkmcnt(12)
	v_mfma_f32_16x16x32_bf16 v[218:221], v[162:165], v[166:169], 0
	s_waitcnt lgkmcnt(10)
	v_mfma_f32_16x16x32_bf16 v[80:83], v[170:173], v[174:177], 0
	s_waitcnt lgkmcnt(8)
	v_mfma_f32_16x16x32_bf16 v[222:225], v[178:181], v[182:185], 0
	s_waitcnt lgkmcnt(6)
	v_mfma_f32_16x16x32_bf16 v[76:79], v[186:189], v[190:193], 0
	s_waitcnt lgkmcnt(4)
	v_mfma_f32_16x16x32_bf16 v[226:229], v[194:197], v[198:201], 0
	s_waitcnt lgkmcnt(2)
	v_mfma_f32_16x16x32_bf16 v[72:75], v[202:205], v[206:209], 0
	s_waitcnt lgkmcnt(0)
	v_mfma_f32_16x16x32_bf16 v[230:233], v[210:213], v[214:217], 0
	v_xor_b32_e32 v0, 0x80000000, v219
	v_xor_b32_e32 v1, 0x80000000, v218
	v_cvt_pk_bf16_f32 v0, v1, v0
	v_xor_b32_e32 v1, 0x80000000, v220
	v_xor_b32_e32 v84, 0x80000000, v221
	v_cvt_pk_bf16_f32 v1, v1, v84
	ds_write_b64 v92, v[0:1]
	v_xor_b32_e32 v0, 0x80000000, v223
	v_xor_b32_e32 v1, 0x80000000, v222
	v_cvt_pk_bf16_f32 v0, v1, v0
	v_xor_b32_e32 v1, 0x80000000, v224
	v_xor_b32_e32 v84, 0x80000000, v225
	v_cvt_pk_bf16_f32 v1, v1, v84
	ds_write_b64 v92, v[0:1] offset:4352
	v_xor_b32_e32 v0, 0x80000000, v227
	v_xor_b32_e32 v1, 0x80000000, v226
	v_cvt_pk_bf16_f32 v0, v1, v0
	v_xor_b32_e32 v1, 0x80000000, v228
	v_xor_b32_e32 v84, 0x80000000, v229
	v_cvt_pk_bf16_f32 v1, v1, v84
	ds_write_b64 v92, v[0:1] offset:8704
	v_xor_b32_e32 v0, 0x80000000, v231
	v_xor_b32_e32 v1, 0x80000000, v230
	v_cvt_pk_bf16_f32 v0, v1, v0
	v_xor_b32_e32 v1, 0x80000000, v232
	v_xor_b32_e32 v84, 0x80000000, v233
	v_cvt_pk_bf16_f32 v1, v1, v84
	ds_write_b64 v92, v[0:1] offset:13056
	v_add_u32_e32 v0, 0, v140
	s_waitcnt lgkmcnt(0)
	v_add_u32_e32 v106, 0x24a80, v0
	v_add_u32_e32 v102, 0x24b80, v0
	v_mul_u32_u24_e32 v0, 0x88, v137
	v_lshl_add_u32 v0, v0, 1, v108
	s_waitcnt lgkmcnt(0)
	s_barrier
	v_mov_b32_e32 v218, 0
	v_mov_b32_e32 v219, 0
	v_mov_b32_e32 v234, 0
	v_mov_b32_e32 v235, 0
	v_mov_b32_e32 v242, 0
	v_mov_b32_e32 v243, 0
	v_mov_b32_e32 v246, 0
	v_mov_b32_e32 v247, 0
	v_mov_b32_e32 v250, s76
	ds_read_b128 v[236:239], v250 offset:768
	ds_read_b64 v[154:155], v0
	ds_read_b64 v[156:157], v0 offset:32
	ds_read_b64 v[170:171], v0 offset:17408
	ds_read_b64 v[172:173], v0 offset:17440
	ds_read_b64 v[158:159], v0 offset:64
	ds_read_b64 v[160:161], v0 offset:96
	ds_read_b64 v[174:175], v0 offset:17472
	ds_read_b64 v[176:177], v0 offset:17504
	v_mad_u32_u24 v252, v137, s84, v101
	v_lshlrev_b32_e32 v92, 1, v137
	v_mul_u32_u24_e32 v93, 0x440, v138
	v_add3_u32 v253, s89, v92, v93
	v_cvt_pk_bf16_f32 v186, v36, v37
	v_cvt_pk_bf16_f32 v187, v38, v39
	v_cvt_pk_bf16_f32 v188, v40, v41
	v_cvt_pk_bf16_f32 v189, v42, v43
	ds_read_b64 v[162:163], v0 offset:128
	ds_read_b64 v[164:165], v0 offset:160
	ds_read_b64 v[178:179], v0 offset:17536
	ds_read_b64 v[180:181], v0 offset:17568
	s_waitcnt lgkmcnt(8)
	v_mfma_f32_16x16x32_bf16 v[68:71], v[154:157], v[186:189], v[68:71]
	v_mfma_f32_16x16x32_bf16 v[84:87], v[170:173], v[186:189], 0
	v_cvt_pk_bf16_f32 v190, v44, v45
	v_cvt_pk_bf16_f32 v191, v46, v47
	v_cvt_pk_bf16_f32 v192, v48, v49
	v_cvt_pk_bf16_f32 v193, v50, v51
	ds_read_b64 v[166:167], v0 offset:192
	ds_read_b64 v[168:169], v0 offset:224
	ds_read_b64 v[182:183], v0 offset:17600
	ds_read_b64 v[184:185], v0 offset:17632
	s_waitcnt lgkmcnt(8)
	v_mfma_f32_16x16x32_bf16 v[68:71], v[158:161], v[190:193], v[68:71]
	v_mfma_f32_16x16x32_bf16 v[84:87], v[174:177], v[190:193], v[84:87]
	v_cvt_pk_bf16_f32 v194, v52, v53
	v_cvt_pk_bf16_f32 v195, v54, v55
	v_cvt_pk_bf16_f32 v196, v56, v57
	v_cvt_pk_bf16_f32 v197, v58, v59
	ds_read_b64 v[202:203], v103 offset:34816
	ds_read_b64 v[204:205], v104 offset:34816
	ds_read_b64 v[206:207], v104 offset:37376
	ds_read_b64 v[208:209], v104 offset:39936
	s_waitcnt lgkmcnt(8)
	v_mfma_f32_16x16x32_bf16 v[68:71], v[162:165], v[194:197], v[68:71]
	v_mfma_f32_16x16x32_bf16 v[84:87], v[178:181], v[194:197], v[84:87]
	v_cvt_pk_bf16_f32 v198, v60, v61
	v_cvt_pk_bf16_f32 v199, v62, v63
	v_cvt_pk_bf16_f32 v200, v64, v65
	v_cvt_pk_bf16_f32 v201, v66, v67
	ds_read_b64 v[210:211], v103 offset:45056
	ds_read_b64 v[212:213], v103 offset:47616
	ds_read_b64 v[214:215], v103 offset:50176
	ds_read_b64 v[216:217], v103 offset:52736
	s_waitcnt lgkmcnt(8)
; #define LAS __attribute__((address_space(3)))
; __device__ __forceinline__ void phase_gdn2(Frame& F, bool ctx_out, bool dry = false) {
;     ...
;                 for (int I = 0; I < 4; ++I) {
;                     f32x4 vn = U[I], oa = (f32x4){0.f, 0.f, 0.f, 0.f};
; #pragma unroll
;                     for (int ks = 0; ks < 4; ++ks) {
;                         const v4u sb4 = (v4u){pk2(S[2 * ks].x, S[2 * ks].y), pk2(S[2 * ks].z, S[2 * ks].w), pk2(S[2 * ks + 1].x, S[2 * ks + 1].y), pk2(S[2 * ks + 1].z, S[2 * ks + 1].w)};
;                         const hb8 fb = __builtin_bit_cast(hb8, sb4);
;                         const v2u w0 = *(const LAS v2u*)(W + (I * 16 + l15) * GS + ks * 32 + q4 * 4), w1 = *(const LAS v2u*)(W + (I * 16 + l15) * GS + ks * 32 + 16 + q4 * 4);
;                         const v2u q0 = *(const LAS v2u*)(QC + (I * 16 + l15) * GS + ks * 32 + q4 * 4), q1 = *(const LAS v2u*)(QC + (I * 16 + l15) * GS + ks * 32 + 16 + q4 * 4);
;                         const v4u fw4 = (v4u){w0.x, w0.y, w1.x, w1.y}, fq4 = (v4u){q0.x, q0.y, q1.x, q1.y};
;                         vn = MFMA16(__builtin_bit_cast(hb8, fw4), fb, vn); oa = MFMA16(__builtin_bit_cast(hb8, fq4), fb, oa); }
;                     const f32x4 ck = *(const LAS f32x4*)(s_ckd + I * 16 + q4 * 4), eg = *(const LAS f32x4*)(s_eG + I * 16 + q4 * 4), rqv = *(const LAS f32x4*)(s_rq + I * 16 + q4 * 4);
;                     const v4u vn4 = (v4u){pk2(vn.x, vn.y), pk2(vn.z, vn.w), 0u, 0u}, vp4 = (v4u){pk2(vn.x * ck.x, vn.y * ck.y), pk2(vn.z * ck.z, vn.w * ck.w), 0u, 0u};
;                     oa = oa * eg;
;                     { const v2u a0 = *(const LAS v2u*)(QKB + (I * 16 + l15) * GB + q4 * 4); const v4u fa4 = (v4u){a0.x, a0.y, 0u, 0u}; oa = MFMA16(__builtin_bit_cast(hb8, fa4), __builtin_bit_cast(hb8, vn4), oa); }
;                     oa = oa * rqv;
; #pragma unroll
;                     for (int i = 0; i < 4; ++i) O16[(I * 16 + q4 * 4 + i) * GS + vb * 16 + l15] = (bf16)f2bf(oa[i]);
;                     const float ege = s_eGend[I];
;                     const hb8 fbn = __builtin_bit_cast(hb8, vp4);
; #pragma unroll
;                     for (int kt = 0; kt < 8; ++kt) { const v2u a0 = *(const LAS v2u*)(KCT + (kt * 16 + l15) * GT + I * 16 + q4 * 4); const v4u fa4 = (v4u){a0.x, a0.y, 0u, 0u}; S[kt] = MFMA16(__builtin_bit_cast(hb8, fa4), fbn, S[kt] * ege); }
;                 }
	v_mfma_f32_16x16x32_bf16 v[68:71], v[166:169], v[198:201], v[68:71]
	v_mfma_f32_16x16x32_bf16 v[84:87], v[182:185], v[198:201], v[84:87]
	ds_read_b128 v[220:223], v106
	ds_read_b128 v[224:227], v107 offset:512
	ds_read_b128 v[228:231], v102
	ds_read_b64 v[232:233], v252
	v_pk_mul_f32 v[36:37], v[36:37], v[236:237] op_sel_hi:[1,0]
	v_pk_mul_f32 v[38:39], v[38:39], v[236:237] op_sel_hi:[1,0]
	v_pk_mul_f32 v[40:41], v[40:41], v[236:237] op_sel_hi:[1,0]
	v_pk_mul_f32 v[42:43], v[42:43], v[236:237] op_sel_hi:[1,0]
	v_pk_mul_f32 v[44:45], v[44:45], v[236:237] op_sel_hi:[1,0]
	v_pk_mul_f32 v[46:47], v[46:47], v[236:237] op_sel_hi:[1,0]
	v_pk_mul_f32 v[48:49], v[48:49], v[236:237] op_sel_hi:[1,0]
	v_pk_mul_f32 v[50:51], v[50:51], v[236:237] op_sel_hi:[1,0]
	v_pk_mul_f32 v[52:53], v[52:53], v[236:237] op_sel_hi:[1,0]
	v_pk_mul_f32 v[54:55], v[54:55], v[236:237] op_sel_hi:[1,0]
	v_pk_mul_f32 v[56:57], v[56:57], v[236:237] op_sel_hi:[1,0]
	v_pk_mul_f32 v[58:59], v[58:59], v[236:237] op_sel_hi:[1,0]
	v_pk_mul_f32 v[60:61], v[60:61], v[236:237] op_sel_hi:[1,0]
	v_pk_mul_f32 v[62:63], v[62:63], v[236:237] op_sel_hi:[1,0]
	v_pk_mul_f32 v[64:65], v[64:65], v[236:237] op_sel_hi:[1,0]
	v_pk_mul_f32 v[66:67], v[66:67], v[236:237] op_sel_hi:[1,0]
	s_waitcnt lgkmcnt(2)
	v_cvt_pk_bf16_f32 v240, v68, v69
	v_cvt_pk_bf16_f32 v241, v70, v71
	v_pk_mul_f32 v[88:89], v[68:69], v[220:221]
	v_pk_mul_f32 v[90:91], v[70:71], v[222:223]
	v_cvt_pk_bf16_f32 v244, v88, v89
	v_cvt_pk_bf16_f32 v245, v90, v91
	v_pk_mul_f32 v[84:85], v[84:85], v[224:225]
	v_pk_mul_f32 v[86:87], v[86:87], v[226:227]
	s_waitcnt lgkmcnt(0)
	v_mfma_f32_16x16x32_bf16 v[36:39], v[202:205], v[244:247], v[36:39]
	v_mfma_f32_16x16x32_bf16 v[40:43], v[204:207], v[244:247], v[40:43]
	v_mfma_f32_16x16x32_bf16 v[84:87], v[232:235], v[240:243], v[84:87]
	v_add_u32_e32 v250, 4352, v0
	v_mfma_f32_16x16x32_bf16 v[44:47], v[206:209], v[244:247], v[44:47]
	v_mfma_f32_16x16x32_bf16 v[48:51], v[208:211], v[244:247], v[48:51]
	v_mfma_f32_16x16x32_bf16 v[52:55], v[210:213], v[244:247], v[52:55]
	v_mfma_f32_16x16x32_bf16 v[56:59], v[212:215], v[244:247], v[56:59]
	v_mfma_f32_16x16x32_bf16 v[60:63], v[214:217], v[244:247], v[60:63]
	v_mfma_f32_16x16x32_bf16 v[64:67], v[216:219], v[244:247], v[64:67]
	ds_read_b64 v[154:155], v250
	ds_read_b64 v[156:157], v250 offset:32
	ds_read_b64 v[170:171], v250 offset:17408
	ds_read_b64 v[172:173], v250 offset:17440
	ds_read_b64 v[158:159], v250 offset:64
	ds_read_b64 v[160:161], v250 offset:96
	ds_read_b64 v[174:175], v250 offset:17472
	ds_read_b64 v[176:177], v250 offset:17504
	v_pk_mul_f32 v[84:85], v[84:85], v[228:229]
	v_pk_mul_f32 v[86:87], v[86:87], v[230:231]
	v_cvt_pk_bf16_f32 v88, v84, v85
	v_cvt_pk_bf16_f32 v90, v86, v87
	v_lshrrev_b32_e32 v89, 16, v88
	v_lshrrev_b32_e32 v91, 16, v90
	ds_write_b16 v253, v88
	ds_write_b16 v253, v89 offset:272
	ds_write_b16 v253, v90 offset:544
	ds_write_b16 v253, v91 offset:816
	v_cvt_pk_bf16_f32 v186, v36, v37
	v_cvt_pk_bf16_f32 v187, v38, v39
	v_cvt_pk_bf16_f32 v188, v40, v41
	v_cvt_pk_bf16_f32 v189, v42, v43
	s_waitcnt lgkmcnt(8)
	ds_read_b64 v[162:163], v250 offset:128
	ds_read_b64 v[164:165], v250 offset:160
	ds_read_b64 v[178:179], v250 offset:17536
	ds_read_b64 v[180:181], v250 offset:17568
	s_waitcnt lgkmcnt(8)
	v_mfma_f32_16x16x32_bf16 v[80:83], v[154:157], v[186:189], v[80:83]
	v_mfma_f32_16x16x32_bf16 v[84:87], v[170:173], v[186:189], 0
	v_cvt_pk_bf16_f32 v190, v44, v45
	v_cvt_pk_bf16_f32 v191, v46, v47
	v_cvt_pk_bf16_f32 v192, v48, v49
	v_cvt_pk_bf16_f32 v193, v50, v51
	ds_read_b64 v[166:167], v250 offset:192
	ds_read_b64 v[168:169], v250 offset:224
	ds_read_b64 v[182:183], v250 offset:17600
	ds_read_b64 v[184:185], v250 offset:17632
	s_waitcnt lgkmcnt(8)
	v_mfma_f32_16x16x32_bf16 v[80:83], v[158:161], v[190:193], v[80:83]
	v_mfma_f32_16x16x32_bf16 v[84:87], v[174:177], v[190:193], v[84:87]
	v_cvt_pk_bf16_f32 v194, v52, v53
	v_cvt_pk_bf16_f32 v195, v54, v55
	v_cvt_pk_bf16_f32 v196, v56, v57
	v_cvt_pk_bf16_f32 v197, v58, v59
	ds_read_b64 v[202:203], v103 offset:34848
	ds_read_b64 v[204:205], v104 offset:34848
	ds_read_b64 v[206:207], v104 offset:37408
	ds_read_b64 v[208:209], v104 offset:39968
	s_waitcnt lgkmcnt(8)
	v_mfma_f32_16x16x32_bf16 v[80:83], v[162:165], v[194:197], v[80:83]
	v_mfma_f32_16x16x32_bf16 v[84:87], v[178:181], v[194:197], v[84:87]
	v_cvt_pk_bf16_f32 v198, v60, v61
	v_cvt_pk_bf16_f32 v199, v62, v63
	v_cvt_pk_bf16_f32 v200, v64, v65
	v_cvt_pk_bf16_f32 v201, v66, v67
	ds_read_b64 v[210:211], v103 offset:45088
	ds_read_b64 v[212:213], v103 offset:47648
	ds_read_b64 v[214:215], v103 offset:50208
	ds_read_b64 v[216:217], v103 offset:52768
	s_waitcnt lgkmcnt(8)
	v_mfma_f32_16x16x32_bf16 v[80:83], v[166:169], v[198:201], v[80:83]
	v_mfma_f32_16x16x32_bf16 v[84:87], v[182:185], v[198:201], v[84:87]
	ds_read_b128 v[220:223], v106 offset:64
	ds_read_b128 v[224:227], v107 offset:576
	ds_read_b128 v[228:231], v102 offset:64
	ds_read_b64 v[232:233], v252 offset:1280
	v_pk_mul_f32 v[36:37], v[36:37], v[236:237] op_sel:[0,1]
	v_pk_mul_f32 v[38:39], v[38:39], v[236:237] op_sel:[0,1]
	v_pk_mul_f32 v[40:41], v[40:41], v[236:237] op_sel:[0,1]
	v_pk_mul_f32 v[42:43], v[42:43], v[236:237] op_sel:[0,1]
	v_pk_mul_f32 v[44:45], v[44:45], v[236:237] op_sel:[0,1]
	v_pk_mul_f32 v[46:47], v[46:47], v[236:237] op_sel:[0,1]
	v_pk_mul_f32 v[48:49], v[48:49], v[236:237] op_sel:[0,1]
	v_pk_mul_f32 v[50:51], v[50:51], v[236:237] op_sel:[0,1]
	v_pk_mul_f32 v[52:53], v[52:53], v[236:237] op_sel:[0,1]
	v_pk_mul_f32 v[54:55], v[54:55], v[236:237] op_sel:[0,1]
	v_pk_mul_f32 v[56:57], v[56:57], v[236:237] op_sel:[0,1]
	v_pk_mul_f32 v[58:59], v[58:59], v[236:237] op_sel:[0,1]
	v_pk_mul_f32 v[60:61], v[60:61], v[236:237] op_sel:[0,1]
	v_pk_mul_f32 v[62:63], v[62:63], v[236:237] op_sel:[0,1]
	v_pk_mul_f32 v[64:65], v[64:65], v[236:237] op_sel:[0,1]
	v_pk_mul_f32 v[66:67], v[66:67], v[236:237] op_sel:[0,1]
	s_waitcnt lgkmcnt(2)
; #define LAS __attribute__((address_space(3)))
; __device__ __forceinline__ void phase_gdn2(Frame& F, bool ctx_out, bool dry = false) {
;     ...
;                 for (int I = 0; I < 4; ++I) {
;                     f32x4 vn = U[I], oa = (f32x4){0.f, 0.f, 0.f, 0.f};
; #pragma unroll
;                     for (int ks = 0; ks < 4; ++ks) {
;                         const v4u sb4 = (v4u){pk2(S[2 * ks].x, S[2 * ks].y), pk2(S[2 * ks].z, S[2 * ks].w), pk2(S[2 * ks + 1].x, S[2 * ks + 1].y), pk2(S[2 * ks + 1].z, S[2 * ks + 1].w)};
;                         const hb8 fb = __builtin_bit_cast(hb8, sb4);
;                         const v2u w0 = *(const LAS v2u*)(W + (I * 16 + l15) * GS + ks * 32 + q4 * 4), w1 = *(const LAS v2u*)(W + (I * 16 + l15) * GS + ks * 32 + 16 + q4 * 4);
;                         const v2u q0 = *(const LAS v2u*)(QC + (I * 16 + l15) * GS + ks * 32 + q4 * 4), q1 = *(const LAS v2u*)(QC + (I * 16 + l15) * GS + ks * 32 + 16 + q4 * 4);
;                         const v4u fw4 = (v4u){w0.x, w0.y, w1.x, w1.y}, fq4 = (v4u){q0.x, q0.y, q1.x, q1.y};
;                         vn = MFMA16(__builtin_bit_cast(hb8, fw4), fb, vn); oa = MFMA16(__builtin_bit_cast(hb8, fq4), fb, oa); }
;                     const f32x4 ck = *(const LAS f32x4*)(s_ckd + I * 16 + q4 * 4), eg = *(const LAS f32x4*)(s_eG + I * 16 + q4 * 4), rqv = *(const LAS f32x4*)(s_rq + I * 16 + q4 * 4);
;                     const v4u vn4 = (v4u){pk2(vn.x, vn.y), pk2(vn.z, vn.w), 0u, 0u}, vp4 = (v4u){pk2(vn.x * ck.x, vn.y * ck.y), pk2(vn.z * ck.z, vn.w * ck.w), 0u, 0u};
;                     oa = oa * eg;
;                     { const v2u a0 = *(const LAS v2u*)(QKB + (I * 16 + l15) * GB + q4 * 4); const v4u fa4 = (v4u){a0.x, a0.y, 0u, 0u}; oa = MFMA16(__builtin_bit_cast(hb8, fa4), __builtin_bit_cast(hb8, vn4), oa); }
;                     oa = oa * rqv;
; #pragma unroll
;                     for (int i = 0; i < 4; ++i) O16[(I * 16 + q4 * 4 + i) * GS + vb * 16 + l15] = (bf16)f2bf(oa[i]);
;                     const float ege = s_eGend[I];
;                     const hb8 fbn = __builtin_bit_cast(hb8, vp4);
; #pragma unroll
;                     for (int kt = 0; kt < 8; ++kt) { const v2u a0 = *(const LAS v2u*)(KCT + (kt * 16 + l15) * GT + I * 16 + q4 * 4); const v4u fa4 = (v4u){a0.x, a0.y, 0u, 0u}; S[kt] = MFMA16(__builtin_bit_cast(hb8, fa4), fbn, S[kt] * ege); }
;                 }
	v_cvt_pk_bf16_f32 v240, v80, v81
	v_cvt_pk_bf16_f32 v241, v82, v83
	v_pk_mul_f32 v[88:89], v[80:81], v[220:221]
	v_pk_mul_f32 v[90:91], v[82:83], v[222:223]
	v_cvt_pk_bf16_f32 v244, v88, v89
	v_cvt_pk_bf16_f32 v245, v90, v91
	v_pk_mul_f32 v[84:85], v[84:85], v[224:225]
	v_pk_mul_f32 v[86:87], v[86:87], v[226:227]
	s_waitcnt lgkmcnt(0)
	v_mfma_f32_16x16x32_bf16 v[36:39], v[202:205], v[244:247], v[36:39]
	v_mfma_f32_16x16x32_bf16 v[40:43], v[204:207], v[244:247], v[40:43]
	v_mfma_f32_16x16x32_bf16 v[84:87], v[232:235], v[240:243], v[84:87]
	v_add_u32_e32 v250, 8704, v0
	v_mfma_f32_16x16x32_bf16 v[44:47], v[206:209], v[244:247], v[44:47]
	v_mfma_f32_16x16x32_bf16 v[48:51], v[208:211], v[244:247], v[48:51]
	v_mfma_f32_16x16x32_bf16 v[52:55], v[210:213], v[244:247], v[52:55]
	v_mfma_f32_16x16x32_bf16 v[56:59], v[212:215], v[244:247], v[56:59]
	v_mfma_f32_16x16x32_bf16 v[60:63], v[214:217], v[244:247], v[60:63]
	v_mfma_f32_16x16x32_bf16 v[64:67], v[216:219], v[244:247], v[64:67]
	ds_read_b64 v[154:155], v250
	ds_read_b64 v[156:157], v250 offset:32
	ds_read_b64 v[170:171], v250 offset:17408
	ds_read_b64 v[172:173], v250 offset:17440
	ds_read_b64 v[158:159], v250 offset:64
	ds_read_b64 v[160:161], v250 offset:96
	ds_read_b64 v[174:175], v250 offset:17472
	ds_read_b64 v[176:177], v250 offset:17504
	v_pk_mul_f32 v[84:85], v[84:85], v[228:229]
	v_pk_mul_f32 v[86:87], v[86:87], v[230:231]
	v_cvt_pk_bf16_f32 v88, v84, v85
	v_cvt_pk_bf16_f32 v90, v86, v87
	v_lshrrev_b32_e32 v89, 16, v88
	v_lshrrev_b32_e32 v91, 16, v90
	ds_write_b16 v253, v88 offset:4352
	ds_write_b16 v253, v89 offset:4624
	ds_write_b16 v253, v90 offset:4896
	ds_write_b16 v253, v91 offset:5168
	v_cvt_pk_bf16_f32 v186, v36, v37
	v_cvt_pk_bf16_f32 v187, v38, v39
	v_cvt_pk_bf16_f32 v188, v40, v41
	v_cvt_pk_bf16_f32 v189, v42, v43
	s_waitcnt lgkmcnt(8)
	ds_read_b64 v[162:163], v250 offset:128
	ds_read_b64 v[164:165], v250 offset:160
	ds_read_b64 v[178:179], v250 offset:17536
	ds_read_b64 v[180:181], v250 offset:17568
	s_waitcnt lgkmcnt(8)
	v_mfma_f32_16x16x32_bf16 v[76:79], v[154:157], v[186:189], v[76:79]
	v_mfma_f32_16x16x32_bf16 v[84:87], v[170:173], v[186:189], 0
	v_cvt_pk_bf16_f32 v190, v44, v45
	v_cvt_pk_bf16_f32 v191, v46, v47
	v_cvt_pk_bf16_f32 v192, v48, v49
	v_cvt_pk_bf16_f32 v193, v50, v51
	ds_read_b64 v[166:167], v250 offset:192
	ds_read_b64 v[168:169], v250 offset:224
	ds_read_b64 v[182:183], v250 offset:17600
	ds_read_b64 v[184:185], v250 offset:17632
	s_waitcnt lgkmcnt(8)
	v_mfma_f32_16x16x32_bf16 v[76:79], v[158:161], v[190:193], v[76:79]
	v_mfma_f32_16x16x32_bf16 v[84:87], v[174:177], v[190:193], v[84:87]
	v_cvt_pk_bf16_f32 v194, v52, v53
	v_cvt_pk_bf16_f32 v195, v54, v55
	v_cvt_pk_bf16_f32 v196, v56, v57
	v_cvt_pk_bf16_f32 v197, v58, v59
	ds_read_b64 v[202:203], v103 offset:34880
	ds_read_b64 v[204:205], v104 offset:34880
	ds_read_b64 v[206:207], v104 offset:37440
	ds_read_b64 v[208:209], v104 offset:40000
	s_waitcnt lgkmcnt(8)
	v_mfma_f32_16x16x32_bf16 v[76:79], v[162:165], v[194:197], v[76:79]
	v_mfma_f32_16x16x32_bf16 v[84:87], v[178:181], v[194:197], v[84:87]
	v_cvt_pk_bf16_f32 v198, v60, v61
	v_cvt_pk_bf16_f32 v199, v62, v63
	v_cvt_pk_bf16_f32 v200, v64, v65
	v_cvt_pk_bf16_f32 v201, v66, v67
	ds_read_b64 v[210:211], v103 offset:45120
	ds_read_b64 v[212:213], v103 offset:47680
	ds_read_b64 v[214:215], v103 offset:50240
	ds_read_b64 v[216:217], v103 offset:52800
	s_waitcnt lgkmcnt(8)
	v_mfma_f32_16x16x32_bf16 v[76:79], v[166:169], v[198:201], v[76:79]
	v_mfma_f32_16x16x32_bf16 v[84:87], v[182:185], v[198:201], v[84:87]
	ds_read_b128 v[220:223], v106 offset:128
	ds_read_b128 v[224:227], v107 offset:640
	ds_read_b128 v[228:231], v102 offset:128
	ds_read_b64 v[232:233], v252 offset:2560
	v_pk_mul_f32 v[36:37], v[36:37], v[238:239] op_sel_hi:[1,0]
	v_pk_mul_f32 v[38:39], v[38:39], v[238:239] op_sel_hi:[1,0]
	v_pk_mul_f32 v[40:41], v[40:41], v[238:239] op_sel_hi:[1,0]
	v_pk_mul_f32 v[42:43], v[42:43], v[238:239] op_sel_hi:[1,0]
	v_pk_mul_f32 v[44:45], v[44:45], v[238:239] op_sel_hi:[1,0]
	v_pk_mul_f32 v[46:47], v[46:47], v[238:239] op_sel_hi:[1,0]
	v_pk_mul_f32 v[48:49], v[48:49], v[238:239] op_sel_hi:[1,0]
	v_pk_mul_f32 v[50:51], v[50:51], v[238:239] op_sel_hi:[1,0]
	v_pk_mul_f32 v[52:53], v[52:53], v[238:239] op_sel_hi:[1,0]
	v_pk_mul_f32 v[54:55], v[54:55], v[238:239] op_sel_hi:[1,0]
	v_pk_mul_f32 v[56:57], v[56:57], v[238:239] op_sel_hi:[1,0]
	v_pk_mul_f32 v[58:59], v[58:59], v[238:239] op_sel_hi:[1,0]
	v_pk_mul_f32 v[60:61], v[60:61], v[238:239] op_sel_hi:[1,0]
	v_pk_mul_f32 v[62:63], v[62:63], v[238:239] op_sel_hi:[1,0]
	v_pk_mul_f32 v[64:65], v[64:65], v[238:239] op_sel_hi:[1,0]
	v_pk_mul_f32 v[66:67], v[66:67], v[238:239] op_sel_hi:[1,0]
	s_waitcnt lgkmcnt(2)
	v_cvt_pk_bf16_f32 v240, v76, v77
	v_cvt_pk_bf16_f32 v241, v78, v79
	v_pk_mul_f32 v[88:89], v[76:77], v[220:221]
	v_pk_mul_f32 v[90:91], v[78:79], v[222:223]
	v_cvt_pk_bf16_f32 v244, v88, v89
	v_cvt_pk_bf16_f32 v245, v90, v91
	v_pk_mul_f32 v[84:85], v[84:85], v[224:225]
	v_pk_mul_f32 v[86:87], v[86:87], v[226:227]
	s_waitcnt lgkmcnt(0)
; __device__ __forceinline__ void phase_gdn2(Frame& F, bool ctx_out, bool dry = false) {
;     ...
;                 for (int I = 0; I < 4; ++I) {
;                     f32x4 vn = U[I], oa = (f32x4){0.f, 0.f, 0.f, 0.f};
; #pragma unroll
;                     for (int ks = 0; ks < 4; ++ks) {
;                         const v4u sb4 = (v4u){pk2(S[2 * ks].x, S[2 * ks].y), pk2(S[2 * ks].z, S[2 * ks].w), pk2(S[2 * ks + 1].x, S[2 * ks + 1].y), pk2(S[2 * ks + 1].z, S[2 * ks + 1].w)};
;                         const hb8 fb = __builtin_bit_cast(hb8, sb4);
;                         const v2u w0 = *(const LAS v2u*)(W + (I * 16 + l15) * GS + ks * 32 + q4 * 4), w1 = *(const LAS v2u*)(W + (I * 16 + l15) * GS + ks * 32 + 16 + q4 * 4);
;                         const v2u q0 = *(const LAS v2u*)(QC + (I * 16 + l15) * GS + ks * 32 + q4 * 4), q1 = *(const LAS v2u*)(QC + (I * 16 + l15) * GS + ks * 32 + 16 + q4 * 4);
;                         const v4u fw4 = (v4u){w0.x, w0.y, w1.x, w1.y}, fq4 = (v4u){q0.x, q0.y, q1.x, q1.y};
;                         vn = MFMA16(__builtin_bit_cast(hb8, fw4), fb, vn); oa = MFMA16(__builtin_bit_cast(hb8, fq4), fb, oa); }
;                     const f32x4 ck = *(const LAS f32x4*)(s_ckd + I * 16 + q4 * 4), eg = *(const LAS f32x4*)(s_eG + I * 16 + q4 * 4), rqv = *(const LAS f32x4*)(s_rq + I * 16 + q4 * 4);
;                     const v4u vn4 = (v4u){pk2(vn.x, vn.y), pk2(vn.z, vn.w), 0u, 0u}, vp4 = (v4u){pk2(vn.x * ck.x, vn.y * ck.y), pk2(vn.z * ck.z, vn.w * ck.w), 0u, 0u};
;                     oa = oa * eg;
;                     { const v2u a0 = *(const LAS v2u*)(QKB + (I * 16 + l15) * GB + q4 * 4); const v4u fa4 = (v4u){a0.x, a0.y, 0u, 0u}; oa = MFMA16(__builtin_bit_cast(hb8, fa4), __builtin_bit_cast(hb8, vn4), oa); }
;                     oa = oa * rqv;
; #pragma unroll
;                     for (int i = 0; i < 4; ++i) O16[(I * 16 + q4 * 4 + i) * GS + vb * 16 + l15] = (bf16)f2bf(oa[i]);
;                     const float ege = s_eGend[I];
;                     const hb8 fbn = __builtin_bit_cast(hb8, vp4);
; #pragma unroll
;                     for (int kt = 0; kt < 8; ++kt) { const v2u a0 = *(const LAS v2u*)(KCT + (kt * 16 + l15) * GT + I * 16 + q4 * 4); const v4u fa4 = (v4u){a0.x, a0.y, 0u, 0u}; S[kt] = MFMA16(__builtin_bit_cast(hb8, fa4), fbn, S[kt] * ege); }
;                 }
;                 LDS_BARRIER();
	v_mfma_f32_16x16x32_bf16 v[36:39], v[202:205], v[244:247], v[36:39]
	v_mfma_f32_16x16x32_bf16 v[40:43], v[204:207], v[244:247], v[40:43]
	v_mfma_f32_16x16x32_bf16 v[84:87], v[232:235], v[240:243], v[84:87]
	v_add_u32_e32 v250, 13056, v0
	v_mfma_f32_16x16x32_bf16 v[44:47], v[206:209], v[244:247], v[44:47]
	v_mfma_f32_16x16x32_bf16 v[48:51], v[208:211], v[244:247], v[48:51]
	v_mfma_f32_16x16x32_bf16 v[52:55], v[210:213], v[244:247], v[52:55]
	v_mfma_f32_16x16x32_bf16 v[56:59], v[212:215], v[244:247], v[56:59]
	v_mfma_f32_16x16x32_bf16 v[60:63], v[214:217], v[244:247], v[60:63]
	v_mfma_f32_16x16x32_bf16 v[64:67], v[216:219], v[244:247], v[64:67]
	ds_read_b64 v[154:155], v250
	ds_read_b64 v[156:157], v250 offset:32
	ds_read_b64 v[170:171], v250 offset:17408
	ds_read_b64 v[172:173], v250 offset:17440
	ds_read_b64 v[158:159], v250 offset:64
	ds_read_b64 v[160:161], v250 offset:96
	ds_read_b64 v[174:175], v250 offset:17472
	ds_read_b64 v[176:177], v250 offset:17504
	v_pk_mul_f32 v[84:85], v[84:85], v[228:229]
	v_pk_mul_f32 v[86:87], v[86:87], v[230:231]
	v_cvt_pk_bf16_f32 v88, v84, v85
	v_cvt_pk_bf16_f32 v90, v86, v87
	v_lshrrev_b32_e32 v89, 16, v88
	v_lshrrev_b32_e32 v91, 16, v90
	ds_write_b16 v253, v88 offset:8704
	ds_write_b16 v253, v89 offset:8976
	ds_write_b16 v253, v90 offset:9248
	ds_write_b16 v253, v91 offset:9520
	v_cvt_pk_bf16_f32 v186, v36, v37
	v_cvt_pk_bf16_f32 v187, v38, v39
	v_cvt_pk_bf16_f32 v188, v40, v41
	v_cvt_pk_bf16_f32 v189, v42, v43
	s_waitcnt lgkmcnt(8)
	ds_read_b64 v[162:163], v250 offset:128
	ds_read_b64 v[164:165], v250 offset:160
	ds_read_b64 v[178:179], v250 offset:17536
	ds_read_b64 v[180:181], v250 offset:17568
	s_waitcnt lgkmcnt(8)
	v_mfma_f32_16x16x32_bf16 v[72:75], v[154:157], v[186:189], v[72:75]
	v_mfma_f32_16x16x32_bf16 v[84:87], v[170:173], v[186:189], 0
	v_cvt_pk_bf16_f32 v190, v44, v45
	v_cvt_pk_bf16_f32 v191, v46, v47
	v_cvt_pk_bf16_f32 v192, v48, v49
	v_cvt_pk_bf16_f32 v193, v50, v51
	ds_read_b64 v[166:167], v250 offset:192
	ds_read_b64 v[168:169], v250 offset:224
	ds_read_b64 v[182:183], v250 offset:17600
	ds_read_b64 v[184:185], v250 offset:17632
	s_waitcnt lgkmcnt(8)
	v_mfma_f32_16x16x32_bf16 v[72:75], v[158:161], v[190:193], v[72:75]
	v_mfma_f32_16x16x32_bf16 v[84:87], v[174:177], v[190:193], v[84:87]
	v_cvt_pk_bf16_f32 v194, v52, v53
	v_cvt_pk_bf16_f32 v195, v54, v55
	v_cvt_pk_bf16_f32 v196, v56, v57
	v_cvt_pk_bf16_f32 v197, v58, v59
	ds_read_b64 v[202:203], v103 offset:34912
	ds_read_b64 v[204:205], v104 offset:34912
	ds_read_b64 v[206:207], v104 offset:37472
	ds_read_b64 v[208:209], v104 offset:40032
	s_waitcnt lgkmcnt(8)
	v_mfma_f32_16x16x32_bf16 v[72:75], v[162:165], v[194:197], v[72:75]
	v_mfma_f32_16x16x32_bf16 v[84:87], v[178:181], v[194:197], v[84:87]
	v_cvt_pk_bf16_f32 v198, v60, v61
	v_cvt_pk_bf16_f32 v199, v62, v63
	v_cvt_pk_bf16_f32 v200, v64, v65
	v_cvt_pk_bf16_f32 v201, v66, v67
	ds_read_b64 v[210:211], v103 offset:45152
	ds_read_b64 v[212:213], v103 offset:47712
	ds_read_b64 v[214:215], v103 offset:50272
	ds_read_b64 v[216:217], v103 offset:52832
	s_waitcnt lgkmcnt(8)
	v_mfma_f32_16x16x32_bf16 v[72:75], v[166:169], v[198:201], v[72:75]
	v_mfma_f32_16x16x32_bf16 v[84:87], v[182:185], v[198:201], v[84:87]
	ds_read_b128 v[220:223], v106 offset:192
	ds_read_b128 v[224:227], v107 offset:704
	ds_read_b128 v[228:231], v102 offset:192
	ds_read_b64 v[232:233], v252 offset:3840
	v_pk_mul_f32 v[36:37], v[36:37], v[238:239] op_sel:[0,1]
	v_pk_mul_f32 v[38:39], v[38:39], v[238:239] op_sel:[0,1]
	v_pk_mul_f32 v[40:41], v[40:41], v[238:239] op_sel:[0,1]
	v_pk_mul_f32 v[42:43], v[42:43], v[238:239] op_sel:[0,1]
	v_pk_mul_f32 v[44:45], v[44:45], v[238:239] op_sel:[0,1]
	v_pk_mul_f32 v[46:47], v[46:47], v[238:239] op_sel:[0,1]
	v_pk_mul_f32 v[48:49], v[48:49], v[238:239] op_sel:[0,1]
	v_pk_mul_f32 v[50:51], v[50:51], v[238:239] op_sel:[0,1]
	v_pk_mul_f32 v[52:53], v[52:53], v[238:239] op_sel:[0,1]
	v_pk_mul_f32 v[54:55], v[54:55], v[238:239] op_sel:[0,1]
	v_pk_mul_f32 v[56:57], v[56:57], v[238:239] op_sel:[0,1]
	v_pk_mul_f32 v[58:59], v[58:59], v[238:239] op_sel:[0,1]
	v_pk_mul_f32 v[60:61], v[60:61], v[238:239] op_sel:[0,1]
	v_pk_mul_f32 v[62:63], v[62:63], v[238:239] op_sel:[0,1]
	v_pk_mul_f32 v[64:65], v[64:65], v[238:239] op_sel:[0,1]
	v_pk_mul_f32 v[66:67], v[66:67], v[238:239] op_sel:[0,1]
	s_waitcnt lgkmcnt(2)
	v_cvt_pk_bf16_f32 v240, v72, v73
	v_cvt_pk_bf16_f32 v241, v74, v75
	v_pk_mul_f32 v[88:89], v[72:73], v[220:221]
	v_pk_mul_f32 v[90:91], v[74:75], v[222:223]
	v_cvt_pk_bf16_f32 v244, v88, v89
	v_cvt_pk_bf16_f32 v245, v90, v91
	v_pk_mul_f32 v[84:85], v[84:85], v[224:225]
	v_pk_mul_f32 v[86:87], v[86:87], v[226:227]
	s_waitcnt lgkmcnt(0)
	v_mfma_f32_16x16x32_bf16 v[36:39], v[202:205], v[244:247], v[36:39]
	v_mfma_f32_16x16x32_bf16 v[40:43], v[204:207], v[244:247], v[40:43]
	v_mfma_f32_16x16x32_bf16 v[84:87], v[232:235], v[240:243], v[84:87]
	v_mfma_f32_16x16x32_bf16 v[44:47], v[206:209], v[244:247], v[44:47]
	v_mfma_f32_16x16x32_bf16 v[48:51], v[208:211], v[244:247], v[48:51]
	v_mfma_f32_16x16x32_bf16 v[52:55], v[210:213], v[244:247], v[52:55]
	v_mfma_f32_16x16x32_bf16 v[56:59], v[212:215], v[244:247], v[56:59]
	v_mfma_f32_16x16x32_bf16 v[60:63], v[214:217], v[244:247], v[60:63]
	v_mfma_f32_16x16x32_bf16 v[64:67], v[216:219], v[244:247], v[64:67]
	s_nop 1
	v_pk_mul_f32 v[84:85], v[84:85], v[228:229]
	v_pk_mul_f32 v[86:87], v[86:87], v[230:231]
	v_cvt_pk_bf16_f32 v88, v84, v85
	v_cvt_pk_bf16_f32 v90, v86, v87
	v_lshrrev_b32_e32 v89, 16, v88
	v_lshrrev_b32_e32 v91, 16, v90
	ds_write_b16 v253, v88 offset:13056
	ds_write_b16 v253, v89 offset:13328
	ds_write_b16 v253, v90 offset:13600
	ds_write_b16 v253, v91 offset:13872
	s_waitcnt lgkmcnt(0)
	s_barrier
	s_waitcnt lgkmcnt(0)
	s_cbranch_scc1 .LBB0_1021
